# v24: v23 + tile-boundary group alignment only in the two memory-bound-epilogue GEMMs (W_o and FF2): both groups' residual epilogues share one barrier interval
# baseline (speedup 1.0000x reference)
; #define PG8_STAGE(bufoff, gbase, voff) do { _Pragma("unroll") for (int _i = 0; _i < 2; ++_i) \
;         __builtin_amdgcn_global_load_lds((const unsigned*)((const char*)(gbase) + (voff)[_i]), (LAS unsigned*)(lds + (bufoff) + ldsw + _i * 8192), 16, 0, 0); } while (0)
; #define PG8_WAIT_V(n) asm volatile("s_waitcnt vmcnt(" #n ")" ::: "memory")
; #define PG8_BAR __builtin_amdgcn_s_barrier()
; template <class Epi, class Ptrs>
; __device__ __forceinline__ void gemm_phase(LAS unsigned char* lds, const int K, const StaticOrder& S, const Ptrs& P, const Epi& E) {
;     ...
;     PG8_STAGE(PG8_SB(0, 0), cB, voffB); PG8_STAGE(PG8_SA(0, 0), cA, voffA); PG8_STAGE(PG8_SB(0, 1), cB + hstep, voffB); PG8_STAGE(PG8_SA(0, 1), cA + hstep, voffA);
;     if (wr == 1) PG8_BAR;
;     PG8_WAIT_V(4); PG8_BAR;
;     PG8_STAGE(PG8_SB(1, 0), cB + kstep, voffB); PG8_STAGE(PG8_SA(1, 0), cA + kstep, voffA); PG8_STAGE(PG8_SB(1, 1), cB + hstep + kstep, voffB);
;     PG8_WAIT_V(6); PG8_BAR;
;     __device__ __forceinline__ void operator()(const f32x4 (&acc)[2][2][4][2], const Unit& u, int ui, int wr, int wc, int fr, int fq) const {
;         const int row0 = u.pm * 256 + wr * 64 + fr, col0 = u.pn * 256 + wc * 32 + 8 * fq;
;         const float* xb0 = (u.pm * 256 < MP) ? xp : xs - (size_t)MP * DM;
.LBB0_346:
	s_add_u32 s14, s28, 0x2000000
	s_addc_u32 s15, s29, 0
	s_add_u32 s16, s28, 0x3e000000
	s_addc_u32 s17, s29, 0
	s_ashr_i32 s58, s3, 31
	s_ashr_i32 s59, s2, 31
	s_add_u32 s60, s38, 0xf8000000
	s_mov_b64 s[18:19], 0x80
	s_addc_u32 s61, s39, -1
	s_and_b32 s62, s1, 3
	s_add_i32 m0, s54, 0x18000
	v_lshl_add_u64 v[6:7], v[6:7], 0, s[18:19]
	s_lshl_b32 s1, s0, 13
	s_lshl_b32 s20, s62, 12
	s_waitcnt vmcnt(4)
	s_barrier
	global_load_lds_dwordx4 v[6:7], off
	v_lshl_add_u64 v[4:5], v[4:5], 0, s[18:19]
	s_add_i32 m0, s54, 0x1a000
	s_add_i32 s63, s54, 0x8000
	s_add_i32 s64, s54, 0xa000
	global_load_lds_dwordx4 v[4:5], off
	v_lshl_add_u64 v[2:3], v[2:3], 0, s[18:19]
	s_mov_b32 m0, s63
	s_add_u32 s4, s42, 0x40080
	global_load_lds_dwordx4 v[2:3], off
	v_lshl_add_u64 v[0:1], v[0:1], 0, s[18:19]
	s_mov_b32 m0, s64
	s_addc_u32 s5, s43, 0
	global_load_lds_dwordx4 v[0:1], off
	s_add_i32 m0, s54, 0x1c000
	v_lshl_add_u64 v[0:1], s[4:5], 0, v[178:179]
	global_load_lds_dwordx4 v[0:1], off
	v_lshl_add_u64 v[0:1], s[4:5], 0, v[182:183]
	s_add_i32 m0, s54, 0x1e000
	v_lshlrev_b32_e32 v4, 6, v208
	global_load_lds_dwordx4 v[0:1], off
	v_bfe_u32 v1, v208, 4, 2
	v_lshlrev_b32_e32 v2, 3, v1
	v_lshlrev_b32_e32 v3, 4, v1
	v_cmp_eq_u32_e64 s[6:7], 0, v1
	v_lshlrev_b32_e32 v1, 8, v208
	v_lshl_or_b32 v206, s62, 5, v2
	v_and_b32_e32 v1, 0x38000, v1
	v_lshlrev_b32_e32 v2, 11, v10
	v_or3_b32 v1, v8, v1, v2
	v_and_b32_e32 v0, 15, v208
	s_movk_i32 s4, 0x3c0
	v_lshlrev_b32_e32 v5, 2, v208
	v_add_u32_e32 v184, v1, v9
	v_lshlrev_b32_e32 v1, 4, v11
	v_and_or_b32 v4, v4, s4, v3
	v_and_b32_e32 v5, 32, v5
	v_lshl_or_b32 v204, s0, 6, v0
	v_lshl_or_b32 v0, v0, 6, v3
	s_waitcnt vmcnt(6)
	v_and_b32_e32 v1, 0x78000, v1
	v_bitop3_b32 v0, v0, s1, v5 bitop3:0xde
	v_bitop3_b32 v205, s20, v4, v5 bitop3:0xf6
	v_or3_b32 v1, v8, v1, v2
	s_add_i32 s66, 0, 0x10000
	s_add_i32 s67, 0, 0x14000
	v_mov_b32_e32 v185, v179
	v_add_u32_e32 v186, v1, v9
	v_mov_b32_e32 v187, v179
	v_mov_b64_e32 v[188:189], 0x600
	v_mov_b64_e32 v[190:191], 0x5ff
	s_movk_i32 s65, 0xc1
	v_add_u32_e32 v207, s66, v205
	v_add_u32_e32 v209, 0, v0
	v_add_u32_e32 v210, s67, v205
	s_nop 0
	s_nop 0
	s_nop 0
	s_nop 0
	s_nop 0
	s_nop 0
	s_nop 0
	s_nop 0
	s_nop 0
	s_nop 0
	s_nop 0
	s_nop 0
	s_nop 0
	s_nop 0
	s_nop 0
	s_nop 0
	s_nop 0
	s_nop 0
	s_nop 0
	s_nop 0
	s_nop 0
	s_nop 0
	s_nop 0
	s_nop 0
	s_nop 0
	s_nop 0
	s_nop 0
	s_nop 0
	s_nop 0
	s_nop 0
	s_nop 0
	s_nop 0
	s_nop 0
	s_nop 0
	s_nop 0
	s_nop 0
	s_nop 0
	s_nop 0
	s_nop 0
	s_nop 0
	s_nop 0
	s_nop 0
	s_nop 0
	s_nop 0
	s_nop 0
	s_nop 0
	s_nop 0
	s_nop 0
	s_nop 0
	s_nop 0
	s_nop 0
	s_nop 0
	s_nop 0
	s_nop 0
	s_nop 0
	s_nop 0
	s_nop 0
	s_nop 0
	s_nop 0
	s_mov_b32 s68, 0
	s_cmpk_lt_u32 s46, 0x100
	s_cbranch_scc1 .Lsprio_1
	s_setprio 1
